# scale phase row sum via DPP row ops and v_readlane
# baseline (speedup 1.0000x reference)
.LBB0_130:
	global_load_dwordx4 v[28:31], v32, s[18:19]
	global_load_dwordx4 v[24:27], v32, s[18:19] offset:1024
	global_load_dwordx4 v[20:23], v32, s[18:19] offset:2048
	global_load_dwordx4 v[16:19], v32, s[18:19] offset:3072
	v_lshl_add_u64 v[0:1], s[18:19], 0, v[32:33]
	v_add_co_u32_e32 v0, vcc, s22, v0
	s_waitcnt vmcnt(3)
	v_mul_f32_e32 v60, v29, v29
	v_addc_co_u32_e32 v1, vcc, 0, v1, vcc
	global_load_dwordx4 v[12:15], v[0:1], off
	global_load_dwordx4 v[8:11], v[0:1], off offset:1024
	global_load_dwordx4 v[4:7], v[0:1], off offset:2048
	s_nop 0
	global_load_dwordx4 v[0:3], v[0:1], off offset:3072
	v_mul_f32_e32 v61, v31, v31
	s_waitcnt vmcnt(6)
	v_mul_f32_e32 v62, v25, v25
	v_mul_f32_e32 v63, v27, v27
	s_waitcnt vmcnt(5)
	v_mul_f32_e32 v64, v21, v21
	v_mul_f32_e32 v65, v23, v23
	v_fmac_f32_e32 v60, v28, v28
	v_fmac_f32_e32 v61, v30, v30
	v_fmac_f32_e32 v62, v24, v24
	v_fmac_f32_e32 v63, v26, v26
	s_waitcnt vmcnt(4)
	v_mul_f32_e32 v66, v17, v17
	v_mul_f32_e32 v67, v19, v19
	v_fmac_f32_e32 v64, v20, v20
	v_fmac_f32_e32 v65, v22, v22
	v_add_f32_e32 v60, v60, v61
	v_add_f32_e32 v61, v62, v63
	v_fmac_f32_e32 v66, v16, v16
	v_fmac_f32_e32 v67, v18, v18
	v_add_f32_e32 v62, v64, v65
	v_add_f32_e32 v60, v60, v61
	v_add_f32_e32 v63, v66, v67
	v_add_f32_e32 v60, v60, v62
	v_add_f32_e32 v60, v60, v63
	s_waitcnt vmcnt(3)
	v_mul_f32_e32 v64, v13, v13
	v_mul_f32_e32 v65, v15, v15
	s_waitcnt vmcnt(2)
	v_mul_f32_e32 v66, v9, v9
	v_mul_f32_e32 v67, v11, v11
	v_fmac_f32_e32 v64, v12, v12
	v_fmac_f32_e32 v65, v14, v14
	s_waitcnt vmcnt(1)
	v_mul_f32_e32 v68, v5, v5
	v_mul_f32_e32 v69, v7, v7
	v_fmac_f32_e32 v66, v8, v8
	v_fmac_f32_e32 v67, v10, v10
	v_add_f32_e32 v61, v64, v65
	s_waitcnt vmcnt(0)
	v_mul_f32_e32 v70, v1, v1
	v_mul_f32_e32 v71, v3, v3
	v_fmac_f32_e32 v68, v4, v4
	v_fmac_f32_e32 v69, v6, v6
	v_add_f32_e32 v62, v66, v67
	v_add_f32_e32 v60, v60, v61
	v_fmac_f32_e32 v70, v0, v0
	v_fmac_f32_e32 v71, v2, v2
	v_add_f32_e32 v64, v68, v69
	v_add_f32_e32 v60, v60, v62
	v_add_f32_e32 v60, v60, v64
	v_add_f32_e32 v61, v70, v71
	v_add_f32_e32 v60, v60, v61
	s_waitcnt lgkmcnt(0)
	s_nop 1
	v_add_f32_dpp v60, v60, v60 quad_perm:[1,0,3,2] row_mask:0xf bank_mask:0xf
	s_waitcnt lgkmcnt(0)
	s_nop 1
	v_add_f32_dpp v60, v60, v60 quad_perm:[2,3,0,1] row_mask:0xf bank_mask:0xf
	s_waitcnt lgkmcnt(0)
	s_nop 1
	v_add_f32_dpp v60, v60, v60 row_half_mirror row_mask:0xf bank_mask:0xf
	s_waitcnt lgkmcnt(0)
	s_nop 1
	v_add_f32_dpp v60, v60, v60 row_mirror row_mask:0xf bank_mask:0xf
	s_waitcnt lgkmcnt(0)
	s_nop 0
	v_readlane_b32 s98, v60, 0
	v_readlane_b32 s99, v60, 16
	v_readlane_b32 s100, v60, 32
	v_readlane_b32 s101, v60, 48
	s_nop 1
	v_mov_b32_e32 v61, s100
	v_add_f32_e32 v61, s101, v61
	v_mov_b32_e32 v60, s98
	v_add_f32_e32 v60, s99, v60
	v_add_f32_e32 v60, v60, v61
	s_and_saveexec_b64 s[18:19], s[0:1]
	s_cbranch_execz .LBB0_125
	s_lshl_b64 s[20:21], s[16:17], 2
	s_add_u32 s20, s14, s20
	s_waitcnt lgkmcnt(0)
	s_addc_u32 s21, s15, s21
	global_store_dword v33, v60, s[20:21]
	s_branch .LBB0_125
